# attention row sums with packed f32 adds over register pairs (18 instead of 32 adds per tile)
# speedup vs baseline: 1.0025x; 1.0025x over previous
.Lal1_fast:
	v_exp_f32_e32 v160, v160
	v_exp_f32_e32 v161, v161
	v_exp_f32_e32 v144, v144
	v_exp_f32_e32 v145, v145
	v_exp_f32_e32 v162, v162
	v_exp_f32_e32 v163, v163
	v_exp_f32_e32 v146, v146
	v_exp_f32_e32 v147, v147
	v_pk_add_f32 v[216:217], v[160:161], v[162:163]
	v_pk_add_f32 v[218:219], v[144:145], v[146:147]
	v_exp_f32_e32 v156, v156
	v_exp_f32_e32 v157, v157
	v_exp_f32_e32 v140, v140
	v_exp_f32_e32 v141, v141
	v_pk_add_f32 v[216:217], v[216:217], v[156:157]
	v_pk_add_f32 v[218:219], v[218:219], v[140:141]
	v_exp_f32_e32 v158, v158
	v_exp_f32_e32 v159, v159
	v_exp_f32_e32 v142, v142
	v_exp_f32_e32 v143, v143
	v_pk_add_f32 v[216:217], v[216:217], v[158:159]
	v_pk_add_f32 v[218:219], v[218:219], v[142:143]
	v_exp_f32_e32 v152, v152
	v_exp_f32_e32 v153, v153
	v_exp_f32_e32 v136, v136
	v_exp_f32_e32 v137, v137
	v_pk_add_f32 v[216:217], v[216:217], v[152:153]
	v_pk_add_f32 v[218:219], v[218:219], v[136:137]
	v_exp_f32_e32 v154, v154
	v_exp_f32_e32 v155, v155
	v_exp_f32_e32 v138, v138
	v_exp_f32_e32 v139, v139
	v_pk_add_f32 v[216:217], v[216:217], v[154:155]
	v_pk_add_f32 v[218:219], v[218:219], v[138:139]
	v_exp_f32_e32 v148, v148
	v_exp_f32_e32 v149, v149
	v_exp_f32_e32 v132, v132
	v_exp_f32_e32 v133, v133
	v_pk_add_f32 v[216:217], v[216:217], v[148:149]
	v_pk_add_f32 v[218:219], v[218:219], v[132:133]
	v_exp_f32_e32 v150, v150
	v_exp_f32_e32 v151, v151
	v_exp_f32_e32 v134, v134
	v_exp_f32_e32 v135, v135
	v_pk_add_f32 v[216:217], v[216:217], v[150:151]
	v_pk_add_f32 v[218:219], v[218:219], v[134:135]
	s_nop 0
	v_add_f32_e32 v216, v216, v217
	v_add_f32_e32 v218, v218, v219
	s_nop 0
	v_add_f32_e32 v165, v165, v216
	v_add_f32_e32 v164, v164, v218
	v_cvt_pk_bf16_f32 v160, v160, v161
	v_cvt_pk_bf16_f32 v161, v162, v163
	v_cvt_pk_bf16_f32 v162, v156, v157
	v_cvt_pk_bf16_f32 v163, v158, v159
	v_cvt_pk_bf16_f32 v144, v144, v145
	v_cvt_pk_bf16_f32 v145, v146, v147
	v_cvt_pk_bf16_f32 v146, v140, v141
	v_cvt_pk_bf16_f32 v147, v142, v143
	v_cvt_pk_bf16_f32 v152, v152, v153
	v_cvt_pk_bf16_f32 v153, v154, v155
	v_cvt_pk_bf16_f32 v154, v148, v149
	v_cvt_pk_bf16_f32 v155, v150, v151
	v_cvt_pk_bf16_f32 v136, v136, v137
	v_cvt_pk_bf16_f32 v137, v138, v139
	v_cvt_pk_bf16_f32 v138, v132, v133
	v_cvt_pk_bf16_f32 v139, v134, v135
	s_nop 1
	s_waitcnt lgkmcnt(0)
	v_mfma_f32_16x16x32_bf16 v[96:99], v[100:103], v[160:163], v[96:99]
	v_mfma_f32_16x16x32_bf16 v[16:19], v[100:103], v[144:147], v[16:19]
	v_mfma_f32_16x16x32_bf16 v[28:31], v[108:111], v[160:163], v[28:31]
	v_mfma_f32_16x16x32_bf16 v[12:15], v[108:111], v[144:147], v[12:15]
	v_mfma_f32_16x16x32_bf16 v[24:27], v[120:123], v[160:163], v[24:27]
	v_mfma_f32_16x16x32_bf16 v[8:11], v[120:123], v[144:147], v[8:11]
	v_mfma_f32_16x16x32_bf16 v[20:23], v[128:131], v[160:163], v[20:23]
	v_mfma_f32_16x16x32_bf16 v[4:7], v[128:131], v[144:147], v[4:7]
	v_mfma_f32_16x16x32_bf16 v[96:99], v[104:107], v[152:155], v[96:99]
	v_mfma_f32_16x16x32_bf16 v[16:19], v[104:107], v[136:139], v[16:19]
	v_mfma_f32_16x16x32_bf16 v[28:31], v[112:115], v[152:155], v[28:31]
	v_mfma_f32_16x16x32_bf16 v[12:15], v[112:115], v[136:139], v[12:15]
	v_mfma_f32_16x16x32_bf16 v[24:27], v[124:127], v[152:155], v[24:27]
	v_mfma_f32_16x16x32_bf16 v[8:11], v[124:127], v[136:139], v[8:11]
	v_mfma_f32_16x16x32_bf16 v[20:23], v[116:119], v[152:155], v[20:23]
	v_mfma_f32_16x16x32_bf16 v[4:7], v[116:119], v[136:139], v[4:7]
